# grid barrier: spread generation words (16 lines) plus hierarchical arrival counters (8 groups of 32)
# baseline (speedup 1.0000x reference)
; __device__ __forceinline__ void grid_barrier(unsigned* bar, unsigned& epoch) {
;     asm volatile("s_waitcnt vmcnt(0) lgkmcnt(0)" ::: "memory");
;     __syncthreads();
;     epoch += 1;
;     if (threadIdx.x == 0) {
;         __builtin_amdgcn_fence(__ATOMIC_RELEASE, "agent");
;         asm volatile("s_waitcnt vmcnt(0)" ::: "memory");
;         const unsigned old = __hip_atomic_fetch_add(bar, 1u, __ATOMIC_RELAXED, __HIP_MEMORY_SCOPE_AGENT);
.LBB0_273:
	s_or_b64 exec, exec, s[0:1]
	s_waitcnt vmcnt(0) lgkmcnt(0)
	s_barrier
	v_cmp_eq_u32_e64 s[2:3], 0, v208
	s_mov_b64 s[0:1], exec
	s_nop 0
	v_writelane_b32 v254, s2, 32
	s_nop 1
	v_writelane_b32 v254, s3, 33
	s_and_b64 s[2:3], s[0:1], s[2:3]
	s_mov_b64 exec, s[2:3]
	s_cbranch_execz .LBB0_282
	s_mov_b64 s[2:3], exec
	buffer_wbl2 sc1
	s_waitcnt vmcnt(0)
	s_waitcnt vmcnt(0)
	v_mbcnt_lo_u32_b32 v0, s2, 0
	v_mbcnt_hi_u32_b32 v0, s3, v0
	v_cmp_eq_u32_e32 vcc, 0, v0
	s_and_saveexec_b64 s[4:5], vcc
	s_cbranch_execz .LBB0_276
	s_bcnt1_i32_b64 s2, s[2:3]
	v_mov_b32_e32 v1, 0
	v_mov_b32_e32 v2, s2
	s_cmpk_lg_u32 s45, 0x100
	s_cbranch_scc1 .Lhb_orig_0
	v_readlane_b32 vcc_lo, v253, 0
	s_and_b32 vcc_lo, vcc_lo, 7
	s_lshl_b32 vcc_lo, vcc_lo, 7
	s_addk_i32 vcc_lo, 0x1c00
	v_mov_b32_e32 v0, vcc_lo
	v_mov_b32_e32 v1, 1
	global_atomic_add v1, v0, v1, s[30:31] sc0
	s_waitcnt vmcnt(0)
	v_readfirstlane_b32 vcc_lo, v1
	v_mov_b32_e32 v0, 0
	s_add_i32 vcc_lo, vcc_lo, 1
	s_and_b32 vcc_lo, vcc_lo, 31
	s_cmp_eq_u32 vcc_lo, 0
	s_cbranch_scc1 .Lhb_last_0
	v_mov_b32_e32 v1, 0x7fffff00
	s_branch .LBB0_276

; __device__ __forceinline__ void grid_barrier(unsigned* bar, unsigned& epoch) {
;     asm volatile("s_waitcnt vmcnt(0) lgkmcnt(0)" ::: "memory");
;     __syncthreads();
;     epoch += 1;
;     if (threadIdx.x == 0) {
;         __builtin_amdgcn_fence(__ATOMIC_RELEASE, "agent");
;         asm volatile("s_waitcnt vmcnt(0)" ::: "memory");
;         const unsigned old = __hip_atomic_fetch_add(bar, 1u, __ATOMIC_RELAXED, __HIP_MEMORY_SCOPE_AGENT);
.LBB0_289:
	s_or_b64 exec, exec, s[0:1]
	s_waitcnt vmcnt(0) lgkmcnt(0)
	s_barrier
	s_mov_b64 s[0:1], exec
	v_readlane_b32 s2, v254, 32
	v_readlane_b32 s3, v254, 33
	s_and_b64 s[2:3], s[0:1], s[2:3]
	s_mov_b64 exec, s[2:3]
	s_cbranch_execz .LBB0_298
	s_mov_b64 s[2:3], exec
	buffer_wbl2 sc1
	s_waitcnt vmcnt(0)
	s_waitcnt vmcnt(0)
	v_mbcnt_lo_u32_b32 v0, s2, 0
	v_mbcnt_hi_u32_b32 v0, s3, v0
	v_cmp_eq_u32_e32 vcc, 0, v0
	s_and_saveexec_b64 s[4:5], vcc
	s_cbranch_execz .LBB0_292
	s_bcnt1_i32_b64 s2, s[2:3]
	v_mov_b32_e32 v1, 0
	v_mov_b32_e32 v2, s2
	s_cmpk_lg_u32 s45, 0x100
	s_cbranch_scc1 .Lhb_orig_1
	v_readlane_b32 vcc_lo, v253, 0
	s_and_b32 vcc_lo, vcc_lo, 7
	s_lshl_b32 vcc_lo, vcc_lo, 7
	s_addk_i32 vcc_lo, 0x1c00
	v_mov_b32_e32 v0, vcc_lo
	v_mov_b32_e32 v1, 1
	global_atomic_add v1, v0, v1, s[30:31] sc0
	s_waitcnt vmcnt(0)
	v_readfirstlane_b32 vcc_lo, v1
	v_mov_b32_e32 v0, 0
	s_add_i32 vcc_lo, vcc_lo, 1
	s_and_b32 vcc_lo, vcc_lo, 31
	s_cmp_eq_u32 vcc_lo, 0
	s_cbranch_scc1 .Lhb_last_1
	v_mov_b32_e32 v1, 0x7fffff00
	s_branch .LBB0_292

; __device__ __forceinline__ void grid_barrier(unsigned* bar, unsigned& epoch) {
;     asm volatile("s_waitcnt vmcnt(0) lgkmcnt(0)" ::: "memory");
;     __syncthreads();
;     epoch += 1;
;     if (threadIdx.x == 0) {
;         __builtin_amdgcn_fence(__ATOMIC_RELEASE, "agent");
;         asm volatile("s_waitcnt vmcnt(0)" ::: "memory");
;         const unsigned old = __hip_atomic_fetch_add(bar, 1u, __ATOMIC_RELAXED, __HIP_MEMORY_SCOPE_AGENT);
.LBB0_365:
	s_waitcnt vmcnt(0) lgkmcnt(0)
	s_waitcnt vmcnt(0)
	s_barrier
	s_mov_b64 s[2:3], exec
	v_readlane_b32 s4, v254, 32
	v_readlane_b32 s5, v254, 33
	s_and_b64 s[4:5], s[2:3], s[4:5]
	s_mov_b64 exec, s[4:5]
	s_cbranch_execz .LBB0_374
	s_mov_b64 s[4:5], exec
	buffer_wbl2 sc1
	s_waitcnt vmcnt(0)
	v_mbcnt_lo_u32_b32 v0, s4, 0
	v_mbcnt_hi_u32_b32 v0, s5, v0
	v_cmp_eq_u32_e32 vcc, 0, v0
	s_and_saveexec_b64 s[6:7], vcc
	s_cbranch_execz .LBB0_368
	s_bcnt1_i32_b64 s4, s[4:5]
	v_mov_b32_e32 v1, s4
	v_readlane_b32 s4, v254, 35
	v_readlane_b32 s5, v254, 36
	s_nop 4
	s_cmpk_lg_u32 s45, 0x100
	s_cbranch_scc1 .Lhb_orig_2
	v_readlane_b32 vcc_lo, v253, 0
	s_and_b32 vcc_lo, vcc_lo, 7
	s_lshl_b32 vcc_lo, vcc_lo, 7
	s_addk_i32 vcc_lo, 0x1c00
	v_mov_b32_e32 v0, vcc_lo
	v_mov_b32_e32 v1, 1
	global_atomic_add v1, v0, v1, s[4:5] sc0
	s_waitcnt vmcnt(0)
	v_readfirstlane_b32 vcc_lo, v1
	v_mov_b32_e32 v0, 0
	s_add_i32 vcc_lo, vcc_lo, 1
	s_and_b32 vcc_lo, vcc_lo, 31
	s_cmp_eq_u32 vcc_lo, 0
	s_cbranch_scc1 .Lhb_last_2
	v_mov_b32_e32 v1, 0x7fffff00
	s_branch .LBB0_368

; __device__ __forceinline__ void grid_barrier(unsigned* bar, unsigned& epoch) {
;     asm volatile("s_waitcnt vmcnt(0) lgkmcnt(0)" ::: "memory");
;     __syncthreads();
;     epoch += 1;
;     if (threadIdx.x == 0) {
;         __builtin_amdgcn_fence(__ATOMIC_RELEASE, "agent");
;         asm volatile("s_waitcnt vmcnt(0)" ::: "memory");
;         const unsigned old = __hip_atomic_fetch_add(bar, 1u, __ATOMIC_RELAXED, __HIP_MEMORY_SCOPE_AGENT);
.LBB0_386:
	s_waitcnt vmcnt(0) lgkmcnt(0)
	s_barrier
	s_mov_b64 s[2:3], exec
	v_readlane_b32 s4, v254, 32
	v_readlane_b32 s5, v254, 33
	s_and_b64 s[4:5], s[2:3], s[4:5]
	s_mov_b64 exec, s[4:5]
	s_cbranch_execz .LBB0_395
	s_mov_b64 s[4:5], exec
	buffer_wbl2 sc1
	s_waitcnt vmcnt(0)
	s_waitcnt vmcnt(0)
	v_mbcnt_lo_u32_b32 v0, s4, 0
	v_mbcnt_hi_u32_b32 v0, s5, v0
	v_cmp_eq_u32_e32 vcc, 0, v0
	s_and_saveexec_b64 s[6:7], vcc
	s_cbranch_execz .LBB0_389
	s_bcnt1_i32_b64 s4, s[4:5]
	v_mov_b32_e32 v1, s4
	v_readlane_b32 s4, v254, 35
	v_readlane_b32 s5, v254, 36
	s_nop 4
	s_cmpk_lg_u32 s45, 0x100
	s_cbranch_scc1 .Lhb_orig_3
	v_readlane_b32 vcc_lo, v253, 0
	s_and_b32 vcc_lo, vcc_lo, 7
	s_lshl_b32 vcc_lo, vcc_lo, 7
	s_addk_i32 vcc_lo, 0x1c00
	v_mov_b32_e32 v0, vcc_lo
	v_mov_b32_e32 v1, 1
	global_atomic_add v1, v0, v1, s[4:5] sc0
	s_waitcnt vmcnt(0)
	v_readfirstlane_b32 vcc_lo, v1
	v_mov_b32_e32 v0, 0
	s_add_i32 vcc_lo, vcc_lo, 1
	s_and_b32 vcc_lo, vcc_lo, 31
	s_cmp_eq_u32 vcc_lo, 0
	s_cbranch_scc1 .Lhb_last_3
	v_mov_b32_e32 v1, 0x7fffff00
	s_branch .LBB0_389

; __device__ __forceinline__ void grid_barrier(unsigned* bar, unsigned& epoch) {
;     asm volatile("s_waitcnt vmcnt(0) lgkmcnt(0)" ::: "memory");
;     __syncthreads();
;     epoch += 1;
;     if (threadIdx.x == 0) {
;         __builtin_amdgcn_fence(__ATOMIC_RELEASE, "agent");
;         asm volatile("s_waitcnt vmcnt(0)" ::: "memory");
;         const unsigned old = __hip_atomic_fetch_add(bar, 1u, __ATOMIC_RELAXED, __HIP_MEMORY_SCOPE_AGENT);
.LBB0_504:
	s_waitcnt vmcnt(0) lgkmcnt(0)
	s_waitcnt vmcnt(0) lgkmcnt(0)
	s_barrier
	s_mov_b64 s[2:3], exec
	v_readlane_b32 s4, v254, 32
	v_readlane_b32 s5, v254, 33
	s_and_b64 s[4:5], s[2:3], s[4:5]
	s_mov_b64 exec, s[4:5]
	s_cbranch_execz .LBB0_513
	s_mov_b64 s[4:5], exec
	buffer_wbl2 sc1
	s_waitcnt vmcnt(0)
	v_mbcnt_lo_u32_b32 v0, s4, 0
	v_mbcnt_hi_u32_b32 v0, s5, v0
	v_cmp_eq_u32_e32 vcc, 0, v0
	s_and_saveexec_b64 s[6:7], vcc
	s_cbranch_execz .LBB0_507
	s_bcnt1_i32_b64 s4, s[4:5]
	v_mov_b32_e32 v1, s4
	v_readlane_b32 s4, v254, 35
	v_readlane_b32 s5, v254, 36
	s_nop 4
	s_cmpk_lg_u32 s45, 0x100
	s_cbranch_scc1 .Lhb_orig_4
	v_readlane_b32 vcc_lo, v253, 0
	s_and_b32 vcc_lo, vcc_lo, 7
	s_lshl_b32 vcc_lo, vcc_lo, 7
	s_addk_i32 vcc_lo, 0x1c00
	v_mov_b32_e32 v0, vcc_lo
	v_mov_b32_e32 v1, 1
	global_atomic_add v1, v0, v1, s[4:5] sc0
	s_waitcnt vmcnt(0)
	v_readfirstlane_b32 vcc_lo, v1
	v_mov_b32_e32 v0, 0
	s_add_i32 vcc_lo, vcc_lo, 1
	s_and_b32 vcc_lo, vcc_lo, 31
	s_cmp_eq_u32 vcc_lo, 0
	s_cbranch_scc1 .Lhb_last_4
	v_mov_b32_e32 v1, 0x7fffff00
	s_branch .LBB0_507

; __device__ __forceinline__ void grid_barrier(unsigned* bar, unsigned& epoch) {
;     asm volatile("s_waitcnt vmcnt(0) lgkmcnt(0)" ::: "memory");
;     __syncthreads();
;     epoch += 1;
;     if (threadIdx.x == 0) {
;         __builtin_amdgcn_fence(__ATOMIC_RELEASE, "agent");
;         asm volatile("s_waitcnt vmcnt(0)" ::: "memory");
;         const unsigned old = __hip_atomic_fetch_add(bar, 1u, __ATOMIC_RELAXED, __HIP_MEMORY_SCOPE_AGENT);
.LBB0_636:
	s_waitcnt vmcnt(0) lgkmcnt(0)
	s_barrier
	s_mov_b64 s[2:3], exec
	v_readlane_b32 s4, v254, 32
	v_readlane_b32 s5, v254, 33
	s_and_b64 s[4:5], s[2:3], s[4:5]
	s_mov_b64 s[58:59], 0x380
	s_mov_b64 s[60:61], 0x100
	s_mov_b64 s[62:63], 0x200
	s_mov_b64 s[64:65], 0x280
	s_mov_b64 exec, s[4:5]
	s_cbranch_execz .LBB0_645
	s_mov_b64 s[4:5], exec
	buffer_wbl2 sc1
	s_waitcnt vmcnt(0)
	s_waitcnt vmcnt(0)
	v_mbcnt_lo_u32_b32 v0, s4, 0
	v_mbcnt_hi_u32_b32 v0, s5, v0
	v_cmp_eq_u32_e32 vcc, 0, v0
	s_and_saveexec_b64 s[6:7], vcc
	s_cbranch_execz .LBB0_639
	s_bcnt1_i32_b64 s4, s[4:5]
	v_mov_b32_e32 v1, s4
	v_readlane_b32 s4, v254, 35
	v_readlane_b32 s5, v254, 36
	s_nop 4
	s_cmpk_lg_u32 s45, 0x100
	s_cbranch_scc1 .Lhb_orig_5
	v_readlane_b32 vcc_lo, v253, 0
	s_and_b32 vcc_lo, vcc_lo, 7
	s_lshl_b32 vcc_lo, vcc_lo, 7
	s_addk_i32 vcc_lo, 0x1c00
	v_mov_b32_e32 v0, vcc_lo
	v_mov_b32_e32 v1, 1
	global_atomic_add v1, v0, v1, s[4:5] sc0
	s_waitcnt vmcnt(0)
	v_readfirstlane_b32 vcc_lo, v1
	v_mov_b32_e32 v0, 0
	s_add_i32 vcc_lo, vcc_lo, 1
	s_and_b32 vcc_lo, vcc_lo, 31
	s_cmp_eq_u32 vcc_lo, 0
	s_cbranch_scc1 .Lhb_last_5
	v_mov_b32_e32 v1, 0x7fffff00
	s_branch .LBB0_639

; __device__ __forceinline__ void grid_barrier(unsigned* bar, unsigned& epoch) {
;     asm volatile("s_waitcnt vmcnt(0) lgkmcnt(0)" ::: "memory");
;     __syncthreads();
;     epoch += 1;
;     if (threadIdx.x == 0) {
;         __builtin_amdgcn_fence(__ATOMIC_RELEASE, "agent");
;         asm volatile("s_waitcnt vmcnt(0)" ::: "memory");
;         const unsigned old = __hip_atomic_fetch_add(bar, 1u, __ATOMIC_RELAXED, __HIP_MEMORY_SCOPE_AGENT);
.LBB0_990:
	s_waitcnt vmcnt(0) lgkmcnt(0)
	s_waitcnt lgkmcnt(0)
	s_barrier
	s_mov_b64 s[2:3], exec
	v_readlane_b32 s4, v254, 32
	v_readlane_b32 s5, v254, 33
	s_and_b64 s[4:5], s[2:3], s[4:5]
	s_mov_b64 exec, s[4:5]
	s_cbranch_execz .LBB0_999
	s_mov_b64 s[4:5], exec
	buffer_wbl2 sc1
	s_waitcnt vmcnt(0)
	s_waitcnt vmcnt(0)
	v_mbcnt_lo_u32_b32 v0, s4, 0
	v_mbcnt_hi_u32_b32 v0, s5, v0
	v_cmp_eq_u32_e32 vcc, 0, v0
	s_and_saveexec_b64 s[6:7], vcc
	s_cbranch_execz .LBB0_993
	s_bcnt1_i32_b64 s4, s[4:5]
	v_mov_b32_e32 v1, s4
	v_readlane_b32 s4, v254, 35
	v_readlane_b32 s5, v254, 36
	s_nop 4
	s_cmpk_lg_u32 s45, 0x100
	s_cbranch_scc1 .Lhb_orig_8
	v_readlane_b32 vcc_lo, v253, 0
	s_and_b32 vcc_lo, vcc_lo, 7
	s_lshl_b32 vcc_lo, vcc_lo, 7
	s_addk_i32 vcc_lo, 0x1c00
	v_mov_b32_e32 v0, vcc_lo
	v_mov_b32_e32 v1, 1
	global_atomic_add v1, v0, v1, s[4:5] sc0
	s_waitcnt vmcnt(0)
	v_readfirstlane_b32 vcc_lo, v1
	v_mov_b32_e32 v0, 0
	s_add_i32 vcc_lo, vcc_lo, 1
	s_and_b32 vcc_lo, vcc_lo, 31
	s_cmp_eq_u32 vcc_lo, 0
	s_cbranch_scc1 .Lhb_last_8
	v_mov_b32_e32 v1, 0x7fffff00
	s_branch .LBB0_993

; __device__ __forceinline__ void grid_barrier(unsigned* bar, unsigned& epoch) {
;     asm volatile("s_waitcnt vmcnt(0) lgkmcnt(0)" ::: "memory");
;     __syncthreads();
;     epoch += 1;
;     if (threadIdx.x == 0) {
;         __builtin_amdgcn_fence(__ATOMIC_RELEASE, "agent");
;         asm volatile("s_waitcnt vmcnt(0)" ::: "memory");
;         const unsigned old = __hip_atomic_fetch_add(bar, 1u, __ATOMIC_RELAXED, __HIP_MEMORY_SCOPE_AGENT);
.LBB0_1004:
	s_or_b64 exec, exec, s[42:43]
	s_waitcnt vmcnt(0) lgkmcnt(0)
	s_barrier
	s_mov_b64 s[42:43], exec
	v_readlane_b32 s2, v254, 32
	v_readlane_b32 s3, v254, 33
	s_and_b64 s[2:3], s[42:43], s[2:3]
	s_mov_b64 exec, s[2:3]
	s_cbranch_execz .LBB0_1013
	s_mov_b64 s[46:47], exec
	buffer_wbl2 sc1
	s_waitcnt vmcnt(0)
	s_waitcnt vmcnt(0)
	v_mbcnt_lo_u32_b32 v0, s46, 0
	v_mbcnt_hi_u32_b32 v0, s47, v0
	v_cmp_eq_u32_e32 vcc, 0, v0
	s_and_saveexec_b64 s[48:49], vcc
	s_cbranch_execz .LBB0_1007
	s_bcnt1_i32_b64 s2, s[46:47]
	v_mov_b32_e32 v1, s2
	v_readlane_b32 s2, v254, 35
	v_readlane_b32 s3, v254, 36
	s_nop 4
	s_cmpk_lg_u32 s45, 0x100
	s_cbranch_scc1 .Lhb_orig_9
	v_readlane_b32 vcc_lo, v253, 0
	s_and_b32 vcc_lo, vcc_lo, 7
	s_lshl_b32 vcc_lo, vcc_lo, 7
	s_addk_i32 vcc_lo, 0x1c00
	v_mov_b32_e32 v0, vcc_lo
	v_mov_b32_e32 v1, 1
	global_atomic_add v1, v0, v1, s[2:3] sc0
	s_waitcnt vmcnt(0)
	v_readfirstlane_b32 vcc_lo, v1
	v_mov_b32_e32 v0, 0
	s_add_i32 vcc_lo, vcc_lo, 1
	s_and_b32 vcc_lo, vcc_lo, 31
	s_cmp_eq_u32 vcc_lo, 0
	s_cbranch_scc1 .Lhb_last_9
	v_mov_b32_e32 v1, 0x7fffff00
	s_branch .LBB0_1007

; __device__ __forceinline__ void grid_barrier(unsigned* bar, unsigned& epoch) {
;     asm volatile("s_waitcnt vmcnt(0) lgkmcnt(0)" ::: "memory");
;     __syncthreads();
;     epoch += 1;
;     if (threadIdx.x == 0) {
;         __builtin_amdgcn_fence(__ATOMIC_RELEASE, "agent");
;         asm volatile("s_waitcnt vmcnt(0)" ::: "memory");
;         const unsigned old = __hip_atomic_fetch_add(bar, 1u, __ATOMIC_RELAXED, __HIP_MEMORY_SCOPE_AGENT);
.LBB0_1045:
	s_waitcnt vmcnt(0) lgkmcnt(0)
	s_waitcnt vmcnt(0)
	s_barrier
	s_mov_b64 s[42:43], exec
	v_readlane_b32 s2, v254, 32
	v_readlane_b32 s3, v254, 33
	s_and_b64 s[2:3], s[42:43], s[2:3]
	s_mov_b64 exec, s[2:3]
	s_cbranch_execz .LBB0_1054
	s_mov_b64 s[46:47], exec
	buffer_wbl2 sc1
	s_waitcnt vmcnt(0)
	v_mbcnt_lo_u32_b32 v0, s46, 0
	v_mbcnt_hi_u32_b32 v0, s47, v0
	v_cmp_eq_u32_e32 vcc, 0, v0
	s_and_saveexec_b64 s[48:49], vcc
	s_cbranch_execz .LBB0_1048
	s_bcnt1_i32_b64 s2, s[46:47]
	v_mov_b32_e32 v1, s2
	v_readlane_b32 s2, v254, 35
	v_readlane_b32 s3, v254, 36
	s_nop 4
	s_cmpk_lg_u32 s45, 0x100
	s_cbranch_scc1 .Lhb_orig_10
	v_readlane_b32 vcc_lo, v253, 0
	s_and_b32 vcc_lo, vcc_lo, 7
	s_lshl_b32 vcc_lo, vcc_lo, 7
	s_addk_i32 vcc_lo, 0x1c00
	v_mov_b32_e32 v0, vcc_lo
	v_mov_b32_e32 v1, 1
	global_atomic_add v1, v0, v1, s[2:3] sc0
	s_waitcnt vmcnt(0)
	v_readfirstlane_b32 vcc_lo, v1
	v_mov_b32_e32 v0, 0
	s_add_i32 vcc_lo, vcc_lo, 1
	s_and_b32 vcc_lo, vcc_lo, 31
	s_cmp_eq_u32 vcc_lo, 0
	s_cbranch_scc1 .Lhb_last_10
	v_mov_b32_e32 v1, 0x7fffff00
	s_branch .LBB0_1048

; __device__ __forceinline__ void grid_barrier(unsigned* bar, unsigned& epoch) {
;     asm volatile("s_waitcnt vmcnt(0) lgkmcnt(0)" ::: "memory");
;     __syncthreads();
;     epoch += 1;
;     if (threadIdx.x == 0) {
;         __builtin_amdgcn_fence(__ATOMIC_RELEASE, "agent");
;         asm volatile("s_waitcnt vmcnt(0)" ::: "memory");
;         const unsigned old = __hip_atomic_fetch_add(bar, 1u, __ATOMIC_RELAXED, __HIP_MEMORY_SCOPE_AGENT);
.LBB0_1113:
	s_waitcnt vmcnt(0) lgkmcnt(0)
	s_add_i32 s18, s82, 10
	s_waitcnt lgkmcnt(0)
	s_barrier
	s_mov_b64 s[4:5], exec
	v_readlane_b32 s2, v254, 32
	v_readlane_b32 s3, v254, 33
	s_and_b64 s[2:3], s[4:5], s[2:3]
	s_movk_i32 s52, 0x200
	s_mov_b64 exec, s[2:3]
	s_cbranch_execz .LBB0_1122
	s_mov_b64 s[6:7], exec
	buffer_wbl2 sc1
	s_waitcnt vmcnt(0)
	s_waitcnt vmcnt(0)
	v_mbcnt_lo_u32_b32 v0, s6, 0
	v_mbcnt_hi_u32_b32 v0, s7, v0
	v_cmp_eq_u32_e32 vcc, 0, v0
	s_and_saveexec_b64 s[42:43], vcc
	s_cbranch_execz .LBB0_1116
	s_bcnt1_i32_b64 s2, s[6:7]
	v_mov_b32_e32 v1, s2
	v_readlane_b32 s2, v254, 35
	v_readlane_b32 s3, v254, 36
	s_nop 4
	s_cmpk_lg_u32 s45, 0x100
	s_cbranch_scc1 .Lhb_orig_11
	v_readlane_b32 vcc_lo, v253, 0
	s_and_b32 vcc_lo, vcc_lo, 7
	s_lshl_b32 vcc_lo, vcc_lo, 7
	s_addk_i32 vcc_lo, 0x1c00
	v_mov_b32_e32 v0, vcc_lo
	v_mov_b32_e32 v1, 1
	global_atomic_add v1, v0, v1, s[2:3] sc0
	s_waitcnt vmcnt(0)
	v_readfirstlane_b32 vcc_lo, v1
	v_mov_b32_e32 v0, 0
	s_add_i32 vcc_lo, vcc_lo, 1
	s_and_b32 vcc_lo, vcc_lo, 31
	s_cmp_eq_u32 vcc_lo, 0
	s_cbranch_scc1 .Lhb_last_11
	v_mov_b32_e32 v1, 0x7fffff00
	s_branch .LBB0_1116

; __device__ __forceinline__ void grid_barrier(unsigned* bar, unsigned& epoch) {
;     asm volatile("s_waitcnt vmcnt(0) lgkmcnt(0)" ::: "memory");
;     __syncthreads();
;     epoch += 1;
;     if (threadIdx.x == 0) {
;         __builtin_amdgcn_fence(__ATOMIC_RELEASE, "agent");
;         asm volatile("s_waitcnt vmcnt(0)" ::: "memory");
;         const unsigned old = __hip_atomic_fetch_add(bar, 1u, __ATOMIC_RELAXED, __HIP_MEMORY_SCOPE_AGENT);
.LBB0_1399:
	s_waitcnt vmcnt(0) lgkmcnt(0)
	s_add_i32 s18, s18, 1
	s_barrier
	s_mov_b64 s[2:3], exec
	v_readlane_b32 s4, v254, 32
	v_readlane_b32 s5, v254, 33
	s_and_b64 s[4:5], s[2:3], s[4:5]
	s_mov_b64 exec, s[4:5]
	s_cbranch_execz .LBB0_1398
	s_mov_b64 s[4:5], exec
	buffer_wbl2 sc1
	s_waitcnt vmcnt(0)
	s_waitcnt vmcnt(0)
	v_mbcnt_lo_u32_b32 v0, s4, 0
	v_mbcnt_hi_u32_b32 v0, s5, v0
	v_cmp_eq_u32_e32 vcc, 0, v0
	s_and_saveexec_b64 s[6:7], vcc
	s_cbranch_execz .LBB0_1402
	s_bcnt1_i32_b64 s4, s[4:5]
	v_mov_b32_e32 v1, s4
	v_readlane_b32 s4, v254, 35
	v_readlane_b32 s5, v254, 36
	s_nop 4
	s_cmpk_lg_u32 s45, 0x100
	s_cbranch_scc1 .Lhb_orig_12
	v_readlane_b32 vcc_lo, v253, 0
	s_and_b32 vcc_lo, vcc_lo, 7
	s_lshl_b32 vcc_lo, vcc_lo, 7
	s_addk_i32 vcc_lo, 0x1c00
	v_mov_b32_e32 v0, vcc_lo
	v_mov_b32_e32 v1, 1
	global_atomic_add v1, v0, v1, s[4:5] sc0
	s_waitcnt vmcnt(0)
	v_readfirstlane_b32 vcc_lo, v1
	v_mov_b32_e32 v0, 0
	s_add_i32 vcc_lo, vcc_lo, 1
	s_and_b32 vcc_lo, vcc_lo, 31
	s_cmp_eq_u32 vcc_lo, 0
	s_cbranch_scc1 .Lhb_last_12
	v_mov_b32_e32 v1, 0x7fffff00
	s_branch .LBB0_1402

; __device__ __forceinline__ void grid_barrier(unsigned* bar, unsigned& epoch) {
;     asm volatile("s_waitcnt vmcnt(0) lgkmcnt(0)" ::: "memory");
;     __syncthreads();
;     epoch += 1;
;     if (threadIdx.x == 0) {
;         __builtin_amdgcn_fence(__ATOMIC_RELEASE, "agent");
;         asm volatile("s_waitcnt vmcnt(0)" ::: "memory");
;         const unsigned old = __hip_atomic_fetch_add(bar, 1u, __ATOMIC_RELAXED, __HIP_MEMORY_SCOPE_AGENT);
.LBB0_1410:
	s_mov_b64 s[4:5], exec
	buffer_wbl2 sc1
	s_waitcnt vmcnt(0)
	s_waitcnt vmcnt(0)
	v_mbcnt_lo_u32_b32 v0, s4, 0
	v_mbcnt_hi_u32_b32 v0, s5, v0
	v_cmp_eq_u32_e32 vcc, 0, v0
	s_and_saveexec_b64 s[6:7], vcc
	s_cbranch_execz .LBB0_1412
	s_bcnt1_i32_b64 s4, s[4:5]
	v_mov_b32_e32 v1, s4
	v_readlane_b32 s4, v254, 35
	v_readlane_b32 s5, v254, 36
	s_nop 4
	s_cmpk_lg_u32 s45, 0x100
	s_cbranch_scc1 .Lhb_orig_13
	v_readlane_b32 vcc_lo, v253, 0
	s_and_b32 vcc_lo, vcc_lo, 7
	s_lshl_b32 vcc_lo, vcc_lo, 7
	s_addk_i32 vcc_lo, 0x1c00
	v_mov_b32_e32 v0, vcc_lo
	v_mov_b32_e32 v1, 1
	global_atomic_add v1, v0, v1, s[4:5] sc0
	s_waitcnt vmcnt(0)
	v_readfirstlane_b32 vcc_lo, v1
	v_mov_b32_e32 v0, 0
	s_add_i32 vcc_lo, vcc_lo, 1
	s_and_b32 vcc_lo, vcc_lo, 31
	s_cmp_eq_u32 vcc_lo, 0
	s_cbranch_scc1 .Lhb_last_13
	v_mov_b32_e32 v1, 0x7fffff00
	s_branch .LBB0_1412
